# combined: one-poller panel rendezvous + P5 SALU DMA addresses + dead setprio pairs removed in the P1/P4/P5/P6' K-loops; XCD-local seams; epilogue rewrites
# speedup vs baseline: 1.0053x; 1.0032x over previous
.LBB0_123:
	ds_read_b128 v[128:131], v190
	ds_read_b128 v[132:135], v190 offset:1024
	ds_read_b128 v[136:139], v190 offset:2048
	ds_read_b128 v[140:143], v190 offset:3072
	ds_read_b128 v[144:147], v191
	ds_read_b128 v[160:163], v191 offset:1024
	ds_read_b128 v[164:167], v191 offset:2048
	s_waitcnt lgkmcnt(0)
	ds_read_b128 v[168:171], v191 offset:3072
	s_add_u32 s4, s0, 0xfff80080
	s_addc_u32 s5, s1, -1
	s_cmp_eq_u32 s78, 28
	s_cselect_b32 s73, s69, s5
	s_cselect_b32 s72, s68, s4
	s_cselect_b32 s5, s71, s67
	s_cselect_b32 s4, s70, s65
	s_add_i32 s94, s33, 0xc000
	v_lshl_add_u64 v[184:185], s[0:1], 0, v[156:157]
	s_mov_b32 m0, s94
	s_add_i32 s95, s33, 0xe000
	ds_read_b128 v[172:175], v192
	ds_read_b128 v[176:179], v192 offset:1024
	ds_read_b128 v[180:183], v192 offset:2048
	ds_read_b128 v[194:197], v192 offset:3072
	ds_read_b128 v[198:201], v192 offset:4096
	ds_read_b128 v[202:205], v192 offset:5120
	ds_read_b128 v[206:209], v192 offset:6144
	ds_read_b128 v[210:213], v192 offset:7168
	global_load_lds_dwordx4 v[184:185], off
	v_lshl_add_u64 v[184:185], s[0:1], 0, v[158:159]
	s_mov_b32 m0, s95
	s_nop 0
	global_load_lds_dwordx4 v[184:185], off
	s_waitcnt vmcnt(8)
	s_waitcnt lgkmcnt(0)
	s_barrier
	s_setprio 1
	s_waitcnt lgkmcnt(0)
	v_mfma_f32_16x16x32_bf16 v[124:127], v[128:131], v[172:175], v[124:127]
	v_mfma_f32_16x16x32_bf16 v[120:123], v[136:139], v[172:175], v[120:123]
	v_mfma_f32_16x16x32_bf16 v[108:111], v[128:131], v[180:183], v[108:111]
	v_mfma_f32_16x16x32_bf16 v[104:107], v[136:139], v[180:183], v[104:107]
	v_mfma_f32_16x16x32_bf16 v[92:95], v[128:131], v[198:201], v[92:95]
	v_mfma_f32_16x16x32_bf16 v[88:91], v[136:139], v[198:201], v[88:91]
	v_mfma_f32_16x16x32_bf16 v[76:79], v[128:131], v[206:209], v[76:79]
	v_mfma_f32_16x16x32_bf16 v[72:75], v[136:139], v[206:209], v[72:75]
	v_mfma_f32_16x16x32_bf16 v[124:127], v[132:135], v[176:179], v[124:127]
	v_mfma_f32_16x16x32_bf16 v[120:123], v[140:143], v[176:179], v[120:123]
	v_mfma_f32_16x16x32_bf16 v[108:111], v[132:135], v[194:197], v[108:111]
	v_mfma_f32_16x16x32_bf16 v[104:107], v[140:143], v[194:197], v[104:107]
	v_mfma_f32_16x16x32_bf16 v[92:95], v[132:135], v[202:205], v[92:95]
	v_mfma_f32_16x16x32_bf16 v[88:91], v[140:143], v[202:205], v[88:91]
	v_mfma_f32_16x16x32_bf16 v[76:79], v[132:135], v[210:213], v[76:79]
	v_mfma_f32_16x16x32_bf16 v[72:75], v[140:143], v[210:213], v[72:75]
	v_mfma_f32_16x16x32_bf16 v[116:119], v[144:147], v[172:175], v[116:119]
	v_mfma_f32_16x16x32_bf16 v[112:115], v[164:167], v[172:175], v[112:115]
	v_mfma_f32_16x16x32_bf16 v[100:103], v[144:147], v[180:183], v[100:103]
	v_mfma_f32_16x16x32_bf16 v[96:99], v[164:167], v[180:183], v[96:99]
	v_mfma_f32_16x16x32_bf16 v[84:87], v[144:147], v[198:201], v[84:87]
	v_mfma_f32_16x16x32_bf16 v[80:83], v[164:167], v[198:201], v[80:83]
	v_mfma_f32_16x16x32_bf16 v[68:71], v[144:147], v[206:209], v[68:71]
	v_mfma_f32_16x16x32_bf16 v[64:67], v[164:167], v[206:209], v[64:67]
	v_mfma_f32_16x16x32_bf16 v[116:119], v[160:163], v[176:179], v[116:119]
	v_mfma_f32_16x16x32_bf16 v[112:115], v[168:171], v[176:179], v[112:115]
	v_mfma_f32_16x16x32_bf16 v[100:103], v[160:163], v[194:197], v[100:103]
	v_mfma_f32_16x16x32_bf16 v[96:99], v[168:171], v[194:197], v[96:99]
	v_mfma_f32_16x16x32_bf16 v[84:87], v[160:163], v[202:205], v[84:87]
	v_mfma_f32_16x16x32_bf16 v[80:83], v[168:171], v[202:205], v[80:83]
	v_mfma_f32_16x16x32_bf16 v[68:71], v[160:163], v[210:213], v[68:71]
	v_mfma_f32_16x16x32_bf16 v[64:67], v[168:171], v[210:213], v[64:67]
	s_setprio 0
	s_barrier
	s_add_i32 s96, s31, s40
	s_add_i32 s97, s96, 0x2000
	v_lshl_add_u64 v[184:185], s[4:5], 0, v[150:151]
	s_mov_b32 m0, s96
	s_add_u32 s26, s4, 0x80000
	ds_read_b128 v[172:175], v192 offset:16384
	ds_read_b128 v[176:179], v192 offset:17408
	ds_read_b128 v[180:183], v192 offset:18432
	ds_read_b128 v[194:197], v192 offset:19456
	ds_read_b128 v[198:201], v192 offset:20480
	ds_read_b128 v[202:205], v192 offset:21504
	ds_read_b128 v[206:209], v192 offset:22528
	ds_read_b128 v[210:213], v192 offset:23552
	global_load_lds_dwordx4 v[184:185], off
	v_lshl_add_u64 v[214:215], s[4:5], 0, v[154:155]
	s_mov_b32 m0, s97
	s_addc_u32 s27, s5, 0
	s_add_i32 s91, s30, s40
	global_load_lds_dwordx4 v[214:215], off
	v_lshl_add_u64 v[216:217], s[26:27], 0, v[150:151]
	s_mov_b32 m0, s91
	v_lshl_add_u64 v[218:219], s[72:73], 0, v[152:153]
	global_load_lds_dwordx4 v[216:217], off
	v_lshl_add_u64 v[216:217], s[26:27], 0, v[154:155]
	s_add_i32 s26, s91, 0x2000
	s_mov_b32 m0, s26
	s_nop 0
	global_load_lds_dwordx4 v[216:217], off
	v_lshl_add_u64 v[216:217], s[72:73], 0, v[148:149]
	s_mov_b32 m0, s33
	s_nop 0
	global_load_lds_dwordx4 v[216:217], off
	s_mov_b32 m0, s88
	s_nop 0
	global_load_lds_dwordx4 v[218:219], off
	s_waitcnt vmcnt(8)
	s_waitcnt lgkmcnt(0)
	s_barrier
	s_setprio 1
	s_waitcnt lgkmcnt(0)
	v_mfma_f32_16x16x32_bf16 v[60:63], v[128:131], v[172:175], v[60:63]
	v_mfma_f32_16x16x32_bf16 v[56:59], v[136:139], v[172:175], v[56:59]
	v_mfma_f32_16x16x32_bf16 v[44:47], v[128:131], v[180:183], v[44:47]
	v_mfma_f32_16x16x32_bf16 v[40:43], v[136:139], v[180:183], v[40:43]
	v_mfma_f32_16x16x32_bf16 v[28:31], v[128:131], v[198:201], v[28:31]
	v_mfma_f32_16x16x32_bf16 v[24:27], v[136:139], v[198:201], v[24:27]
	v_mfma_f32_16x16x32_bf16 v[12:15], v[128:131], v[206:209], v[12:15]
	v_mfma_f32_16x16x32_bf16 v[8:11], v[136:139], v[206:209], v[8:11]
	v_mfma_f32_16x16x32_bf16 v[60:63], v[132:135], v[176:179], v[60:63]
	v_mfma_f32_16x16x32_bf16 v[56:59], v[140:143], v[176:179], v[56:59]
	v_mfma_f32_16x16x32_bf16 v[44:47], v[132:135], v[194:197], v[44:47]
	v_mfma_f32_16x16x32_bf16 v[40:43], v[140:143], v[194:197], v[40:43]
	v_mfma_f32_16x16x32_bf16 v[28:31], v[132:135], v[202:205], v[28:31]
	v_mfma_f32_16x16x32_bf16 v[24:27], v[140:143], v[202:205], v[24:27]
	v_mfma_f32_16x16x32_bf16 v[12:15], v[132:135], v[210:213], v[12:15]
	v_mfma_f32_16x16x32_bf16 v[8:11], v[140:143], v[210:213], v[8:11]
	v_mfma_f32_16x16x32_bf16 v[52:55], v[144:147], v[172:175], v[52:55]
	v_mfma_f32_16x16x32_bf16 v[48:51], v[164:167], v[172:175], v[48:51]
	v_mfma_f32_16x16x32_bf16 v[36:39], v[144:147], v[180:183], v[36:39]
	v_mfma_f32_16x16x32_bf16 v[32:35], v[164:167], v[180:183], v[32:35]
	v_mfma_f32_16x16x32_bf16 v[20:23], v[144:147], v[198:201], v[20:23]
	v_mfma_f32_16x16x32_bf16 v[16:19], v[164:167], v[198:201], v[16:19]
	v_mfma_f32_16x16x32_bf16 v[4:7], v[144:147], v[206:209], v[4:7]
	v_mfma_f32_16x16x32_bf16 v[0:3], v[164:167], v[206:209], v[0:3]
	v_mfma_f32_16x16x32_bf16 v[52:55], v[160:163], v[176:179], v[52:55]
	v_mfma_f32_16x16x32_bf16 v[48:51], v[168:171], v[176:179], v[48:51]
	v_mfma_f32_16x16x32_bf16 v[36:39], v[160:163], v[194:197], v[36:39]
	v_mfma_f32_16x16x32_bf16 v[32:35], v[168:171], v[194:197], v[32:35]
	v_mfma_f32_16x16x32_bf16 v[20:23], v[160:163], v[202:205], v[20:23]
	v_mfma_f32_16x16x32_bf16 v[16:19], v[168:171], v[202:205], v[16:19]
	v_mfma_f32_16x16x32_bf16 v[4:7], v[160:163], v[210:213], v[4:7]
	v_mfma_f32_16x16x32_bf16 v[0:3], v[168:171], v[210:213], v[0:3]
	s_setprio 0
	s_barrier
	s_add_i32 s29, 0, 0x18000
	s_add_i32 s41, 0, 0x1c000
	v_add_u32_e32 v140, s29, v189
	v_add_u32_e32 v168, s41, v189
	ds_read_b128 v[128:131], v140
	ds_read_b128 v[132:135], v140 offset:1024
	ds_read_b128 v[136:139], v140 offset:2048
	ds_read_b128 v[140:143], v140 offset:3072
	ds_read_b128 v[144:147], v168
	ds_read_b128 v[160:163], v168 offset:1024
	ds_read_b128 v[164:167], v168 offset:2048
	ds_read_b128 v[168:171], v168 offset:3072
	s_add_u32 s34, s72, 0x80000
	s_addc_u32 s35, s73, 0
	s_mov_b32 m0, s89
	v_lshl_add_u64 v[220:221], s[34:35], 0, v[148:149]
	ds_read_b128 v[172:175], v192 offset:32768
	ds_read_b128 v[176:179], v192 offset:33792
	ds_read_b128 v[180:183], v192 offset:34816
	ds_read_b128 v[194:197], v192 offset:35840
	ds_read_b128 v[198:201], v192 offset:36864
	ds_read_b128 v[202:205], v192 offset:37888
	ds_read_b128 v[206:209], v192 offset:38912
	ds_read_b128 v[210:213], v192 offset:39936
	global_load_lds_dwordx4 v[220:221], off
	v_lshl_add_u64 v[220:221], s[34:35], 0, v[152:153]
	s_mov_b32 m0, s90
	s_nop 0
	global_load_lds_dwordx4 v[220:221], off
	s_waitcnt vmcnt(8)
	s_waitcnt lgkmcnt(0)
	s_barrier
	s_setprio 1
	s_waitcnt lgkmcnt(0)
	v_mfma_f32_16x16x32_bf16 v[124:127], v[128:131], v[172:175], v[124:127]
	v_mfma_f32_16x16x32_bf16 v[120:123], v[136:139], v[172:175], v[120:123]
	v_mfma_f32_16x16x32_bf16 v[108:111], v[128:131], v[180:183], v[108:111]
	v_mfma_f32_16x16x32_bf16 v[104:107], v[136:139], v[180:183], v[104:107]
	v_mfma_f32_16x16x32_bf16 v[92:95], v[128:131], v[198:201], v[92:95]
	v_mfma_f32_16x16x32_bf16 v[88:91], v[136:139], v[198:201], v[88:91]
	v_mfma_f32_16x16x32_bf16 v[76:79], v[128:131], v[206:209], v[76:79]
	v_mfma_f32_16x16x32_bf16 v[72:75], v[136:139], v[206:209], v[72:75]
	v_mfma_f32_16x16x32_bf16 v[124:127], v[132:135], v[176:179], v[124:127]
	v_mfma_f32_16x16x32_bf16 v[120:123], v[140:143], v[176:179], v[120:123]
	v_mfma_f32_16x16x32_bf16 v[108:111], v[132:135], v[194:197], v[108:111]
	v_mfma_f32_16x16x32_bf16 v[104:107], v[140:143], v[194:197], v[104:107]
	v_mfma_f32_16x16x32_bf16 v[92:95], v[132:135], v[202:205], v[92:95]
	v_mfma_f32_16x16x32_bf16 v[88:91], v[140:143], v[202:205], v[88:91]
	v_mfma_f32_16x16x32_bf16 v[76:79], v[132:135], v[210:213], v[76:79]
	v_mfma_f32_16x16x32_bf16 v[72:75], v[140:143], v[210:213], v[72:75]
	v_mfma_f32_16x16x32_bf16 v[116:119], v[144:147], v[172:175], v[116:119]
	v_mfma_f32_16x16x32_bf16 v[112:115], v[164:167], v[172:175], v[112:115]
	v_mfma_f32_16x16x32_bf16 v[100:103], v[144:147], v[180:183], v[100:103]
	v_mfma_f32_16x16x32_bf16 v[96:99], v[164:167], v[180:183], v[96:99]
	v_mfma_f32_16x16x32_bf16 v[84:87], v[144:147], v[198:201], v[84:87]
	v_mfma_f32_16x16x32_bf16 v[80:83], v[164:167], v[198:201], v[80:83]
	v_mfma_f32_16x16x32_bf16 v[68:71], v[144:147], v[206:209], v[68:71]
	v_mfma_f32_16x16x32_bf16 v[64:67], v[164:167], v[206:209], v[64:67]
	v_mfma_f32_16x16x32_bf16 v[116:119], v[160:163], v[176:179], v[116:119]
	v_mfma_f32_16x16x32_bf16 v[112:115], v[168:171], v[176:179], v[112:115]
	v_mfma_f32_16x16x32_bf16 v[100:103], v[160:163], v[194:197], v[100:103]
	v_mfma_f32_16x16x32_bf16 v[96:99], v[168:171], v[194:197], v[96:99]
	v_mfma_f32_16x16x32_bf16 v[84:87], v[160:163], v[202:205], v[84:87]
	v_mfma_f32_16x16x32_bf16 v[80:83], v[168:171], v[202:205], v[80:83]
	v_mfma_f32_16x16x32_bf16 v[68:71], v[160:163], v[210:213], v[68:71]
	v_mfma_f32_16x16x32_bf16 v[64:67], v[168:171], v[210:213], v[64:67]
	s_setprio 0
	s_barrier
	s_add_i32 s27, s29, s40
	s_add_i32 s34, s27, 0x2000
	v_lshl_add_u64 v[184:185], v[184:185], 0, s[48:49]
	s_mov_b32 m0, s27
	s_add_u32 s4, s4, 0x80080
	ds_read_b128 v[172:175], v192 offset:49152
	ds_read_b128 v[176:179], v192 offset:50176
	ds_read_b128 v[180:183], v192 offset:51200
	ds_read_b128 v[194:197], v192 offset:52224
	ds_read_b128 v[198:201], v192 offset:53248
	ds_read_b128 v[202:205], v192 offset:54272
	ds_read_b128 v[206:209], v192 offset:55296
	ds_read_b128 v[210:213], v192 offset:56320
	global_load_lds_dwordx4 v[184:185], off
	v_lshl_add_u64 v[184:185], v[214:215], 0, s[48:49]
	s_mov_b32 m0, s34
	s_addc_u32 s5, s5, 0
	s_add_i32 s35, s41, s40
	global_load_lds_dwordx4 v[184:185], off
	v_lshl_add_u64 v[184:185], s[4:5], 0, v[150:151]
	s_mov_b32 m0, s35
	s_add_i32 s28, s35, 0x2000
	global_load_lds_dwordx4 v[184:185], off
	v_lshl_add_u64 v[184:185], s[4:5], 0, v[154:155]
	s_mov_b32 m0, s28
	s_nop 0
	global_load_lds_dwordx4 v[184:185], off
	v_lshl_add_u64 v[184:185], v[216:217], 0, s[48:49]
	s_mov_b32 m0, s92
	s_nop 0
	global_load_lds_dwordx4 v[184:185], off
	v_lshl_add_u64 v[184:185], v[218:219], 0, s[48:49]
	s_mov_b32 m0, s93
	s_nop 0
	global_load_lds_dwordx4 v[184:185], off
	s_waitcnt vmcnt(8)
	s_waitcnt lgkmcnt(0)
	s_barrier
	s_setprio 1
	s_waitcnt lgkmcnt(0)
	v_mfma_f32_16x16x32_bf16 v[60:63], v[128:131], v[172:175], v[60:63]
	v_mfma_f32_16x16x32_bf16 v[56:59], v[136:139], v[172:175], v[56:59]
	v_mfma_f32_16x16x32_bf16 v[44:47], v[128:131], v[180:183], v[44:47]
	v_mfma_f32_16x16x32_bf16 v[40:43], v[136:139], v[180:183], v[40:43]
	v_mfma_f32_16x16x32_bf16 v[28:31], v[128:131], v[198:201], v[28:31]
	v_mfma_f32_16x16x32_bf16 v[24:27], v[136:139], v[198:201], v[24:27]
	v_mfma_f32_16x16x32_bf16 v[12:15], v[128:131], v[206:209], v[12:15]
	v_mfma_f32_16x16x32_bf16 v[8:11], v[136:139], v[206:209], v[8:11]
	v_mfma_f32_16x16x32_bf16 v[60:63], v[132:135], v[176:179], v[60:63]
	v_mfma_f32_16x16x32_bf16 v[56:59], v[140:143], v[176:179], v[56:59]
	v_mfma_f32_16x16x32_bf16 v[44:47], v[132:135], v[194:197], v[44:47]
	v_mfma_f32_16x16x32_bf16 v[40:43], v[140:143], v[194:197], v[40:43]
	v_mfma_f32_16x16x32_bf16 v[28:31], v[132:135], v[202:205], v[28:31]
	v_mfma_f32_16x16x32_bf16 v[24:27], v[140:143], v[202:205], v[24:27]
	v_mfma_f32_16x16x32_bf16 v[12:15], v[132:135], v[210:213], v[12:15]
	v_mfma_f32_16x16x32_bf16 v[8:11], v[140:143], v[210:213], v[8:11]
	v_mfma_f32_16x16x32_bf16 v[52:55], v[144:147], v[172:175], v[52:55]
	v_mfma_f32_16x16x32_bf16 v[48:51], v[164:167], v[172:175], v[48:51]
	v_mfma_f32_16x16x32_bf16 v[36:39], v[144:147], v[180:183], v[36:39]
	v_mfma_f32_16x16x32_bf16 v[32:35], v[164:167], v[180:183], v[32:35]
	v_mfma_f32_16x16x32_bf16 v[20:23], v[144:147], v[198:201], v[20:23]
	v_mfma_f32_16x16x32_bf16 v[16:19], v[164:167], v[198:201], v[16:19]
	v_mfma_f32_16x16x32_bf16 v[4:7], v[144:147], v[206:209], v[4:7]
	v_mfma_f32_16x16x32_bf16 v[0:3], v[164:167], v[206:209], v[0:3]
	v_mfma_f32_16x16x32_bf16 v[52:55], v[160:163], v[176:179], v[52:55]
	v_mfma_f32_16x16x32_bf16 v[48:51], v[168:171], v[176:179], v[48:51]
	v_mfma_f32_16x16x32_bf16 v[36:39], v[160:163], v[194:197], v[36:39]
	v_mfma_f32_16x16x32_bf16 v[32:35], v[168:171], v[194:197], v[32:35]
	v_mfma_f32_16x16x32_bf16 v[20:23], v[160:163], v[202:205], v[20:23]
	v_mfma_f32_16x16x32_bf16 v[16:19], v[168:171], v[202:205], v[16:19]
	v_mfma_f32_16x16x32_bf16 v[4:7], v[160:163], v[210:213], v[4:7]
	v_mfma_f32_16x16x32_bf16 v[0:3], v[168:171], v[210:213], v[0:3]
	s_setprio 0
	s_barrier
	s_add_i32 s78, s78, 2
	s_add_u32 s0, s0, 0x100
	s_addc_u32 s1, s1, 0
	s_add_u32 s65, s65, 0x100
	s_addc_u32 s67, s67, 0
	s_cmp_gt_u32 s78, 29
	s_cbranch_scc0 .LBB0_123
	s_and_b64 vcc, exec, s[42:43]
	s_cbranch_vccz .LBB0_126
	s_barrier

.LBB0_413:
	ds_read_b128 v[144:147], v155
	ds_read_b128 v[148:151], v155 offset:1024
	ds_read_b128 v[158:161], v155 offset:2048
	ds_read_b128 v[162:165], v155 offset:3072
	ds_read_b128 v[166:169], v156
	ds_read_b128 v[170:173], v156 offset:1024
	ds_read_b128 v[174:177], v156 offset:2048
	ds_read_b128 v[178:181], v156 offset:3072
	s_add_u32 s21, s50, 0xfff80080
	s_addc_u32 s52, s51, -1
	s_cmp_eq_u32 s45, 28
	s_cselect_b32 s55, s9, s52
	s_cselect_b32 s54, s8, s21
	s_cselect_b32 s53, s43, s25
	s_cselect_b32 s52, s42, s23
	s_mov_b32 m0, s94
	v_lshl_add_u64 v[216:217], s[50:51], 0, v[136:137]
	ds_read_b128 v[182:185], v157
	ds_read_b128 v[188:191], v157 offset:1024
	ds_read_b128 v[192:195], v157 offset:2048
	ds_read_b128 v[196:199], v157 offset:3072
	ds_read_b128 v[200:203], v157 offset:4096
	ds_read_b128 v[204:207], v157 offset:5120
	ds_read_b128 v[208:211], v157 offset:6144
	ds_read_b128 v[212:215], v157 offset:7168
	global_load_lds_dwordx4 v[216:217], off
	v_lshl_add_u64 v[216:217], s[50:51], 0, v[138:139]
	s_mov_b32 m0, s95
	s_nop 0
	global_load_lds_dwordx4 v[216:217], off
	s_waitcnt vmcnt(8)
	s_waitcnt lgkmcnt(0)
	s_barrier
	s_setprio 1
	s_waitcnt lgkmcnt(0)
	v_mfma_f32_16x16x32_bf16 v[124:127], v[144:147], v[182:185], v[124:127]
	v_mfma_f32_16x16x32_bf16 v[120:123], v[158:161], v[182:185], v[120:123]
	v_mfma_f32_16x16x32_bf16 v[108:111], v[144:147], v[192:195], v[108:111]
	v_mfma_f32_16x16x32_bf16 v[104:107], v[158:161], v[192:195], v[104:107]
	v_mfma_f32_16x16x32_bf16 v[92:95], v[144:147], v[200:203], v[92:95]
	v_mfma_f32_16x16x32_bf16 v[88:91], v[158:161], v[200:203], v[88:91]
	v_mfma_f32_16x16x32_bf16 v[76:79], v[144:147], v[208:211], v[76:79]
	v_mfma_f32_16x16x32_bf16 v[72:75], v[158:161], v[208:211], v[72:75]
	v_mfma_f32_16x16x32_bf16 v[124:127], v[148:151], v[188:191], v[124:127]
	v_mfma_f32_16x16x32_bf16 v[120:123], v[162:165], v[188:191], v[120:123]
	v_mfma_f32_16x16x32_bf16 v[108:111], v[148:151], v[196:199], v[108:111]
	v_mfma_f32_16x16x32_bf16 v[104:107], v[162:165], v[196:199], v[104:107]
	v_mfma_f32_16x16x32_bf16 v[92:95], v[148:151], v[204:207], v[92:95]
	v_mfma_f32_16x16x32_bf16 v[88:91], v[162:165], v[204:207], v[88:91]
	v_mfma_f32_16x16x32_bf16 v[76:79], v[148:151], v[212:215], v[76:79]
	v_mfma_f32_16x16x32_bf16 v[72:75], v[162:165], v[212:215], v[72:75]
	v_mfma_f32_16x16x32_bf16 v[116:119], v[166:169], v[182:185], v[116:119]
	v_mfma_f32_16x16x32_bf16 v[112:115], v[174:177], v[182:185], v[112:115]
	v_mfma_f32_16x16x32_bf16 v[100:103], v[166:169], v[192:195], v[100:103]
	v_mfma_f32_16x16x32_bf16 v[96:99], v[174:177], v[192:195], v[96:99]
	v_mfma_f32_16x16x32_bf16 v[84:87], v[166:169], v[200:203], v[84:87]
	v_mfma_f32_16x16x32_bf16 v[80:83], v[174:177], v[200:203], v[80:83]
	v_mfma_f32_16x16x32_bf16 v[68:71], v[166:169], v[208:211], v[68:71]
	v_mfma_f32_16x16x32_bf16 v[64:67], v[174:177], v[208:211], v[64:67]
	v_mfma_f32_16x16x32_bf16 v[116:119], v[170:173], v[188:191], v[116:119]
	v_mfma_f32_16x16x32_bf16 v[112:115], v[178:181], v[188:191], v[112:115]
	v_mfma_f32_16x16x32_bf16 v[100:103], v[170:173], v[196:199], v[100:103]
	v_mfma_f32_16x16x32_bf16 v[96:99], v[178:181], v[196:199], v[96:99]
	v_mfma_f32_16x16x32_bf16 v[84:87], v[170:173], v[204:207], v[84:87]
	v_mfma_f32_16x16x32_bf16 v[80:83], v[178:181], v[204:207], v[80:83]
	v_mfma_f32_16x16x32_bf16 v[68:71], v[170:173], v[212:215], v[68:71]
	v_mfma_f32_16x16x32_bf16 v[64:67], v[178:181], v[212:215], v[64:67]
	s_setprio 0
	s_barrier
	s_mov_b32 m0, s96
	v_lshl_add_u64 v[216:217], s[52:53], 0, v[130:131]
	s_add_u32 s58, s52, 0x80000
	ds_read_b128 v[182:185], v157 offset:16384
	ds_read_b128 v[188:191], v157 offset:17408
	ds_read_b128 v[192:195], v157 offset:18432
	ds_read_b128 v[196:199], v157 offset:19456
	ds_read_b128 v[200:203], v157 offset:20480
	ds_read_b128 v[204:207], v157 offset:21504
	ds_read_b128 v[208:211], v157 offset:22528
	ds_read_b128 v[212:215], v157 offset:23552
	global_load_lds_dwordx4 v[216:217], off
	v_lshl_add_u64 v[218:219], s[52:53], 0, v[134:135]
	s_mov_b32 m0, s97
	s_addc_u32 s59, s53, 0
	global_load_lds_dwordx4 v[218:219], off
	v_lshl_add_u64 v[220:221], s[58:59], 0, v[130:131]
	s_mov_b32 m0, s91
	v_lshl_add_u64 v[222:223], s[54:55], 0, v[132:133]
	global_load_lds_dwordx4 v[220:221], off
	v_lshl_add_u64 v[220:221], s[58:59], 0, v[134:135]
	s_mov_b32 m0, s26
	s_nop 0
	global_load_lds_dwordx4 v[220:221], off
	v_lshl_add_u64 v[220:221], s[54:55], 0, v[128:129]
	s_mov_b32 m0, s33
	s_nop 0
	global_load_lds_dwordx4 v[220:221], off
	s_mov_b32 m0, s88
	s_nop 0
	global_load_lds_dwordx4 v[222:223], off
	s_waitcnt vmcnt(8)
	s_waitcnt lgkmcnt(0)
	s_barrier
	s_setprio 1
	s_waitcnt lgkmcnt(0)
	v_mfma_f32_16x16x32_bf16 v[60:63], v[144:147], v[182:185], v[60:63]
	v_mfma_f32_16x16x32_bf16 v[56:59], v[158:161], v[182:185], v[56:59]
	v_mfma_f32_16x16x32_bf16 v[44:47], v[144:147], v[192:195], v[44:47]
	v_mfma_f32_16x16x32_bf16 v[40:43], v[158:161], v[192:195], v[40:43]
	v_mfma_f32_16x16x32_bf16 v[28:31], v[144:147], v[200:203], v[28:31]
	v_mfma_f32_16x16x32_bf16 v[24:27], v[158:161], v[200:203], v[24:27]
	v_mfma_f32_16x16x32_bf16 v[12:15], v[144:147], v[208:211], v[12:15]
	v_mfma_f32_16x16x32_bf16 v[8:11], v[158:161], v[208:211], v[8:11]
	v_mfma_f32_16x16x32_bf16 v[60:63], v[148:151], v[188:191], v[60:63]
	v_mfma_f32_16x16x32_bf16 v[56:59], v[162:165], v[188:191], v[56:59]
	v_mfma_f32_16x16x32_bf16 v[44:47], v[148:151], v[196:199], v[44:47]
	v_mfma_f32_16x16x32_bf16 v[40:43], v[162:165], v[196:199], v[40:43]
	v_mfma_f32_16x16x32_bf16 v[28:31], v[148:151], v[204:207], v[28:31]
	v_mfma_f32_16x16x32_bf16 v[24:27], v[162:165], v[204:207], v[24:27]
	v_mfma_f32_16x16x32_bf16 v[12:15], v[148:151], v[212:215], v[12:15]
	v_mfma_f32_16x16x32_bf16 v[8:11], v[162:165], v[212:215], v[8:11]
	v_mfma_f32_16x16x32_bf16 v[52:55], v[166:169], v[182:185], v[52:55]
	v_mfma_f32_16x16x32_bf16 v[48:51], v[174:177], v[182:185], v[48:51]
	v_mfma_f32_16x16x32_bf16 v[36:39], v[166:169], v[192:195], v[36:39]
	v_mfma_f32_16x16x32_bf16 v[32:35], v[174:177], v[192:195], v[32:35]
	v_mfma_f32_16x16x32_bf16 v[20:23], v[166:169], v[200:203], v[20:23]
	v_mfma_f32_16x16x32_bf16 v[16:19], v[174:177], v[200:203], v[16:19]
	v_mfma_f32_16x16x32_bf16 v[4:7], v[166:169], v[208:211], v[4:7]
	v_mfma_f32_16x16x32_bf16 v[0:3], v[174:177], v[208:211], v[0:3]
	v_mfma_f32_16x16x32_bf16 v[52:55], v[170:173], v[188:191], v[52:55]
	v_mfma_f32_16x16x32_bf16 v[48:51], v[178:181], v[188:191], v[48:51]
	v_mfma_f32_16x16x32_bf16 v[36:39], v[170:173], v[196:199], v[36:39]
	v_mfma_f32_16x16x32_bf16 v[32:35], v[178:181], v[196:199], v[32:35]
	v_mfma_f32_16x16x32_bf16 v[20:23], v[170:173], v[204:207], v[20:23]
	v_mfma_f32_16x16x32_bf16 v[16:19], v[178:181], v[204:207], v[16:19]
	v_mfma_f32_16x16x32_bf16 v[4:7], v[170:173], v[212:215], v[4:7]
	v_mfma_f32_16x16x32_bf16 v[0:3], v[178:181], v[212:215], v[0:3]
	s_setprio 0
	s_barrier
	v_add_u32_e32 v162, s29, v153
	v_add_u32_e32 v178, s41, v153
	ds_read_b128 v[144:147], v162
	ds_read_b128 v[148:151], v162 offset:1024
	ds_read_b128 v[158:161], v162 offset:2048
	ds_read_b128 v[162:165], v162 offset:3072
	ds_read_b128 v[166:169], v178
	ds_read_b128 v[170:173], v178 offset:1024
	ds_read_b128 v[174:177], v178 offset:2048
	ds_read_b128 v[178:181], v178 offset:3072
	s_add_u32 s54, s54, 0x80000
	s_addc_u32 s55, s55, 0
	s_mov_b32 m0, s89
	v_lshl_add_u64 v[224:225], s[54:55], 0, v[128:129]
	ds_read_b128 v[182:185], v157 offset:32768
	ds_read_b128 v[188:191], v157 offset:33792
	ds_read_b128 v[192:195], v157 offset:34816
	ds_read_b128 v[196:199], v157 offset:35840
	ds_read_b128 v[200:203], v157 offset:36864
	ds_read_b128 v[204:207], v157 offset:37888
	ds_read_b128 v[208:211], v157 offset:38912
	ds_read_b128 v[212:215], v157 offset:39936
	global_load_lds_dwordx4 v[224:225], off
	v_lshl_add_u64 v[224:225], s[54:55], 0, v[132:133]
	s_mov_b32 m0, s90
	s_nop 0
	global_load_lds_dwordx4 v[224:225], off
	s_waitcnt vmcnt(8)
	s_waitcnt lgkmcnt(0)
	s_barrier
	s_setprio 1
	s_waitcnt lgkmcnt(0)
	v_mfma_f32_16x16x32_bf16 v[124:127], v[144:147], v[182:185], v[124:127]
	v_mfma_f32_16x16x32_bf16 v[120:123], v[158:161], v[182:185], v[120:123]
	v_mfma_f32_16x16x32_bf16 v[108:111], v[144:147], v[192:195], v[108:111]
	v_mfma_f32_16x16x32_bf16 v[104:107], v[158:161], v[192:195], v[104:107]
	v_mfma_f32_16x16x32_bf16 v[92:95], v[144:147], v[200:203], v[92:95]
	v_mfma_f32_16x16x32_bf16 v[88:91], v[158:161], v[200:203], v[88:91]
	v_mfma_f32_16x16x32_bf16 v[76:79], v[144:147], v[208:211], v[76:79]
	v_mfma_f32_16x16x32_bf16 v[72:75], v[158:161], v[208:211], v[72:75]
	v_mfma_f32_16x16x32_bf16 v[124:127], v[148:151], v[188:191], v[124:127]
	v_mfma_f32_16x16x32_bf16 v[120:123], v[162:165], v[188:191], v[120:123]
	v_mfma_f32_16x16x32_bf16 v[108:111], v[148:151], v[196:199], v[108:111]
	v_mfma_f32_16x16x32_bf16 v[104:107], v[162:165], v[196:199], v[104:107]
	v_mfma_f32_16x16x32_bf16 v[92:95], v[148:151], v[204:207], v[92:95]
	v_mfma_f32_16x16x32_bf16 v[88:91], v[162:165], v[204:207], v[88:91]
	v_mfma_f32_16x16x32_bf16 v[76:79], v[148:151], v[212:215], v[76:79]
	v_mfma_f32_16x16x32_bf16 v[72:75], v[162:165], v[212:215], v[72:75]
	v_mfma_f32_16x16x32_bf16 v[116:119], v[166:169], v[182:185], v[116:119]
	v_mfma_f32_16x16x32_bf16 v[112:115], v[174:177], v[182:185], v[112:115]
	v_mfma_f32_16x16x32_bf16 v[100:103], v[166:169], v[192:195], v[100:103]
	v_mfma_f32_16x16x32_bf16 v[96:99], v[174:177], v[192:195], v[96:99]
	v_mfma_f32_16x16x32_bf16 v[84:87], v[166:169], v[200:203], v[84:87]
	v_mfma_f32_16x16x32_bf16 v[80:83], v[174:177], v[200:203], v[80:83]
	v_mfma_f32_16x16x32_bf16 v[68:71], v[166:169], v[208:211], v[68:71]
	v_mfma_f32_16x16x32_bf16 v[64:67], v[174:177], v[208:211], v[64:67]
	v_mfma_f32_16x16x32_bf16 v[116:119], v[170:173], v[188:191], v[116:119]
	v_mfma_f32_16x16x32_bf16 v[112:115], v[178:181], v[188:191], v[112:115]
	v_mfma_f32_16x16x32_bf16 v[100:103], v[170:173], v[196:199], v[100:103]
	v_mfma_f32_16x16x32_bf16 v[96:99], v[178:181], v[196:199], v[96:99]
	v_mfma_f32_16x16x32_bf16 v[84:87], v[170:173], v[204:207], v[84:87]
	v_mfma_f32_16x16x32_bf16 v[80:83], v[178:181], v[204:207], v[80:83]
	v_mfma_f32_16x16x32_bf16 v[68:71], v[170:173], v[212:215], v[68:71]
	v_mfma_f32_16x16x32_bf16 v[64:67], v[178:181], v[212:215], v[64:67]
	s_setprio 0
	s_barrier
	s_mov_b32 m0, s27
	v_lshl_add_u64 v[216:217], v[216:217], 0, s[16:17]
	s_add_u32 s52, s52, 0x80080
	ds_read_b128 v[182:185], v157 offset:49152
	ds_read_b128 v[188:191], v157 offset:50176
	ds_read_b128 v[192:195], v157 offset:51200
	ds_read_b128 v[196:199], v157 offset:52224
	ds_read_b128 v[200:203], v157 offset:53248
	ds_read_b128 v[204:207], v157 offset:54272
	ds_read_b128 v[208:211], v157 offset:55296
	ds_read_b128 v[212:215], v157 offset:56320
	global_load_lds_dwordx4 v[216:217], off
	v_lshl_add_u64 v[216:217], v[218:219], 0, s[16:17]
	s_mov_b32 m0, s34
	s_addc_u32 s53, s53, 0
	global_load_lds_dwordx4 v[216:217], off
	v_lshl_add_u64 v[216:217], s[52:53], 0, v[130:131]
	s_mov_b32 m0, s35
	s_nop 0
	global_load_lds_dwordx4 v[216:217], off
	v_lshl_add_u64 v[216:217], s[52:53], 0, v[134:135]
	s_mov_b32 m0, s28
	s_nop 0
	global_load_lds_dwordx4 v[216:217], off
	v_lshl_add_u64 v[216:217], v[220:221], 0, s[16:17]
	s_mov_b32 m0, s92
	s_nop 0
	global_load_lds_dwordx4 v[216:217], off
	v_lshl_add_u64 v[216:217], v[222:223], 0, s[16:17]
	s_mov_b32 m0, s93
	s_nop 0
	global_load_lds_dwordx4 v[216:217], off
	s_waitcnt vmcnt(8)
	s_waitcnt lgkmcnt(0)
	s_barrier
	s_setprio 1
	s_waitcnt lgkmcnt(0)
	v_mfma_f32_16x16x32_bf16 v[60:63], v[144:147], v[182:185], v[60:63]
	v_mfma_f32_16x16x32_bf16 v[56:59], v[158:161], v[182:185], v[56:59]
	v_mfma_f32_16x16x32_bf16 v[44:47], v[144:147], v[192:195], v[44:47]
	v_mfma_f32_16x16x32_bf16 v[40:43], v[158:161], v[192:195], v[40:43]
	v_mfma_f32_16x16x32_bf16 v[28:31], v[144:147], v[200:203], v[28:31]
	v_mfma_f32_16x16x32_bf16 v[24:27], v[158:161], v[200:203], v[24:27]
	v_mfma_f32_16x16x32_bf16 v[12:15], v[144:147], v[208:211], v[12:15]
	v_mfma_f32_16x16x32_bf16 v[8:11], v[158:161], v[208:211], v[8:11]
	v_mfma_f32_16x16x32_bf16 v[60:63], v[148:151], v[188:191], v[60:63]
	v_mfma_f32_16x16x32_bf16 v[56:59], v[162:165], v[188:191], v[56:59]
	v_mfma_f32_16x16x32_bf16 v[44:47], v[148:151], v[196:199], v[44:47]
	v_mfma_f32_16x16x32_bf16 v[40:43], v[162:165], v[196:199], v[40:43]
	v_mfma_f32_16x16x32_bf16 v[28:31], v[148:151], v[204:207], v[28:31]
	v_mfma_f32_16x16x32_bf16 v[24:27], v[162:165], v[204:207], v[24:27]
	v_mfma_f32_16x16x32_bf16 v[12:15], v[148:151], v[212:215], v[12:15]
	v_mfma_f32_16x16x32_bf16 v[8:11], v[162:165], v[212:215], v[8:11]
	v_mfma_f32_16x16x32_bf16 v[52:55], v[166:169], v[182:185], v[52:55]
	v_mfma_f32_16x16x32_bf16 v[48:51], v[174:177], v[182:185], v[48:51]
	v_mfma_f32_16x16x32_bf16 v[36:39], v[166:169], v[192:195], v[36:39]
	v_mfma_f32_16x16x32_bf16 v[32:35], v[174:177], v[192:195], v[32:35]
	v_mfma_f32_16x16x32_bf16 v[20:23], v[166:169], v[200:203], v[20:23]
	v_mfma_f32_16x16x32_bf16 v[16:19], v[174:177], v[200:203], v[16:19]
	v_mfma_f32_16x16x32_bf16 v[4:7], v[166:169], v[208:211], v[4:7]
	v_mfma_f32_16x16x32_bf16 v[0:3], v[174:177], v[208:211], v[0:3]
	v_mfma_f32_16x16x32_bf16 v[52:55], v[170:173], v[188:191], v[52:55]
	v_mfma_f32_16x16x32_bf16 v[48:51], v[178:181], v[188:191], v[48:51]
	v_mfma_f32_16x16x32_bf16 v[36:39], v[170:173], v[196:199], v[36:39]
	v_mfma_f32_16x16x32_bf16 v[32:35], v[178:181], v[196:199], v[32:35]
	v_mfma_f32_16x16x32_bf16 v[20:23], v[170:173], v[204:207], v[20:23]
	v_mfma_f32_16x16x32_bf16 v[16:19], v[178:181], v[204:207], v[16:19]
	v_mfma_f32_16x16x32_bf16 v[4:7], v[170:173], v[212:215], v[4:7]
	v_mfma_f32_16x16x32_bf16 v[0:3], v[178:181], v[212:215], v[0:3]
	s_setprio 0
	s_barrier
	s_add_i32 s45, s45, 2
	s_add_u32 s50, s50, 0x100
	s_addc_u32 s51, s51, 0
	s_add_u32 s23, s23, 0x100
	s_addc_u32 s25, s25, 0
	s_cmp_gt_u32 s45, 29
	s_cbranch_scc0 .LBB0_413
	s_and_b64 vcc, exec, s[78:79]
	s_cbranch_vccz .LBB0_416
	s_barrier

.LBB0_507:
	ds_read_b128 v[166:169], v163
	ds_read_b128 v[170:173], v163 offset:1024
	ds_read_b128 v[174:177], v163 offset:2048
	ds_read_b128 v[178:181], v163 offset:3072
	ds_read_b128 v[182:185], v164
	ds_read_b128 v[188:191], v164 offset:1024
	ds_read_b128 v[192:195], v164 offset:2048
	ds_read_b128 v[196:199], v164 offset:3072
	s_add_u32 s44, s42, 0xfff80080
	s_addc_u32 s45, s43, -1
	s_cmp_eq_u32 s52, 28
	s_cselect_b32 s47, s7, s45
	s_cselect_b32 s46, s6, s44
	s_cselect_b32 s45, s23, s21
	s_cselect_b32 s44, s22, s17
	s_add_u32 s54, s44, 0x80000
	s_addc_u32 s55, s45, 0
	s_mov_b32 m0, s94
	ds_read_b128 v[200:203], v165
	ds_read_b128 v[204:207], v165 offset:1024
	ds_read_b128 v[208:211], v165 offset:2048
	ds_read_b128 v[212:215], v165 offset:3072
	ds_read_b128 v[216:219], v165 offset:4096
	ds_read_b128 v[220:223], v165 offset:5120
	ds_read_b128 v[224:227], v165 offset:6144
	ds_read_b128 v[228:231], v165 offset:7168
	global_load_lds_dwordx4 v152, s[42:43]
	s_mov_b32 m0, s95
	s_nop 0
	global_load_lds_dwordx4 v154, s[42:43]
	s_waitcnt vmcnt(8)
	s_waitcnt lgkmcnt(0)
	s_barrier
	s_setprio 1
	s_waitcnt lgkmcnt(0)
	v_mfma_f32_16x16x32_bf16 v[124:127], v[166:169], v[200:203], v[124:127]
	v_mfma_f32_16x16x32_bf16 v[120:123], v[174:177], v[200:203], v[120:123]
	v_mfma_f32_16x16x32_bf16 v[108:111], v[166:169], v[208:211], v[108:111]
	v_mfma_f32_16x16x32_bf16 v[104:107], v[174:177], v[208:211], v[104:107]
	v_mfma_f32_16x16x32_bf16 v[92:95], v[166:169], v[216:219], v[92:95]
	v_mfma_f32_16x16x32_bf16 v[88:91], v[174:177], v[216:219], v[88:91]
	v_mfma_f32_16x16x32_bf16 v[76:79], v[166:169], v[224:227], v[76:79]
	v_mfma_f32_16x16x32_bf16 v[72:75], v[174:177], v[224:227], v[72:75]
	v_mfma_f32_16x16x32_bf16 v[124:127], v[170:173], v[204:207], v[124:127]
	v_mfma_f32_16x16x32_bf16 v[120:123], v[178:181], v[204:207], v[120:123]
	v_mfma_f32_16x16x32_bf16 v[108:111], v[170:173], v[212:215], v[108:111]
	v_mfma_f32_16x16x32_bf16 v[104:107], v[178:181], v[212:215], v[104:107]
	v_mfma_f32_16x16x32_bf16 v[92:95], v[170:173], v[220:223], v[92:95]
	v_mfma_f32_16x16x32_bf16 v[88:91], v[178:181], v[220:223], v[88:91]
	v_mfma_f32_16x16x32_bf16 v[76:79], v[170:173], v[228:231], v[76:79]
	v_mfma_f32_16x16x32_bf16 v[72:75], v[178:181], v[228:231], v[72:75]
	v_mfma_f32_16x16x32_bf16 v[116:119], v[182:185], v[200:203], v[116:119]
	v_mfma_f32_16x16x32_bf16 v[112:115], v[192:195], v[200:203], v[112:115]
	v_mfma_f32_16x16x32_bf16 v[100:103], v[182:185], v[208:211], v[100:103]
	v_mfma_f32_16x16x32_bf16 v[96:99], v[192:195], v[208:211], v[96:99]
	v_mfma_f32_16x16x32_bf16 v[84:87], v[182:185], v[216:219], v[84:87]
	v_mfma_f32_16x16x32_bf16 v[80:83], v[192:195], v[216:219], v[80:83]
	v_mfma_f32_16x16x32_bf16 v[68:71], v[182:185], v[224:227], v[68:71]
	v_mfma_f32_16x16x32_bf16 v[64:67], v[192:195], v[224:227], v[64:67]
	v_mfma_f32_16x16x32_bf16 v[116:119], v[188:191], v[204:207], v[116:119]
	v_mfma_f32_16x16x32_bf16 v[112:115], v[196:199], v[204:207], v[112:115]
	v_mfma_f32_16x16x32_bf16 v[100:103], v[188:191], v[212:215], v[100:103]
	v_mfma_f32_16x16x32_bf16 v[96:99], v[196:199], v[212:215], v[96:99]
	v_mfma_f32_16x16x32_bf16 v[84:87], v[188:191], v[220:223], v[84:87]
	v_mfma_f32_16x16x32_bf16 v[80:83], v[196:199], v[220:223], v[80:83]
	v_mfma_f32_16x16x32_bf16 v[68:71], v[188:191], v[228:231], v[68:71]
	v_mfma_f32_16x16x32_bf16 v[64:67], v[196:199], v[228:231], v[64:67]
	s_setprio 0
	s_barrier
	s_mov_b32 m0, s96
	s_add_u32 s98, s46, 0x80000
	s_addc_u32 s99, s47, 0
	ds_read_b128 v[200:203], v165 offset:16384
	ds_read_b128 v[204:207], v165 offset:17408
	ds_read_b128 v[208:211], v165 offset:18432
	ds_read_b128 v[212:215], v165 offset:19456
	ds_read_b128 v[216:219], v165 offset:20480
	ds_read_b128 v[220:223], v165 offset:21504
	ds_read_b128 v[224:227], v165 offset:22528
	ds_read_b128 v[228:231], v165 offset:23552
	global_load_lds_dwordx4 v130, s[44:45]
	s_mov_b32 m0, s97
	s_nop 0
	global_load_lds_dwordx4 v134, s[44:45]
	s_mov_b32 m0, s91
	s_nop 0
	global_load_lds_dwordx4 v130, s[54:55]
	s_mov_b32 m0, s26
	s_nop 0
	global_load_lds_dwordx4 v134, s[54:55]
	s_mov_b32 m0, s33
	s_nop 0
	global_load_lds_dwordx4 v128, s[46:47]
	s_mov_b32 m0, s88
	s_nop 0
	global_load_lds_dwordx4 v132, s[46:47]
	s_waitcnt vmcnt(8)
	s_waitcnt lgkmcnt(0)
	s_barrier
	s_setprio 1
	s_waitcnt lgkmcnt(0)
	v_mfma_f32_16x16x32_bf16 v[60:63], v[166:169], v[200:203], v[60:63]
	v_mfma_f32_16x16x32_bf16 v[56:59], v[174:177], v[200:203], v[56:59]
	v_mfma_f32_16x16x32_bf16 v[44:47], v[166:169], v[208:211], v[44:47]
	v_mfma_f32_16x16x32_bf16 v[40:43], v[174:177], v[208:211], v[40:43]
	v_mfma_f32_16x16x32_bf16 v[28:31], v[166:169], v[216:219], v[28:31]
	v_mfma_f32_16x16x32_bf16 v[24:27], v[174:177], v[216:219], v[24:27]
	v_mfma_f32_16x16x32_bf16 v[12:15], v[166:169], v[224:227], v[12:15]
	v_mfma_f32_16x16x32_bf16 v[8:11], v[174:177], v[224:227], v[8:11]
	v_mfma_f32_16x16x32_bf16 v[60:63], v[170:173], v[204:207], v[60:63]
	v_mfma_f32_16x16x32_bf16 v[56:59], v[178:181], v[204:207], v[56:59]
	v_mfma_f32_16x16x32_bf16 v[44:47], v[170:173], v[212:215], v[44:47]
	v_mfma_f32_16x16x32_bf16 v[40:43], v[178:181], v[212:215], v[40:43]
	v_mfma_f32_16x16x32_bf16 v[28:31], v[170:173], v[220:223], v[28:31]
	v_mfma_f32_16x16x32_bf16 v[24:27], v[178:181], v[220:223], v[24:27]
	v_mfma_f32_16x16x32_bf16 v[12:15], v[170:173], v[228:231], v[12:15]
	v_mfma_f32_16x16x32_bf16 v[8:11], v[178:181], v[228:231], v[8:11]
	v_mfma_f32_16x16x32_bf16 v[52:55], v[182:185], v[200:203], v[52:55]
	v_mfma_f32_16x16x32_bf16 v[48:51], v[192:195], v[200:203], v[48:51]
	v_mfma_f32_16x16x32_bf16 v[36:39], v[182:185], v[208:211], v[36:39]
	v_mfma_f32_16x16x32_bf16 v[32:35], v[192:195], v[208:211], v[32:35]
	v_mfma_f32_16x16x32_bf16 v[20:23], v[182:185], v[216:219], v[20:23]
	v_mfma_f32_16x16x32_bf16 v[16:19], v[192:195], v[216:219], v[16:19]
	v_mfma_f32_16x16x32_bf16 v[4:7], v[182:185], v[224:227], v[4:7]
	v_mfma_f32_16x16x32_bf16 v[0:3], v[192:195], v[224:227], v[0:3]
	v_mfma_f32_16x16x32_bf16 v[52:55], v[188:191], v[204:207], v[52:55]
	v_mfma_f32_16x16x32_bf16 v[48:51], v[196:199], v[204:207], v[48:51]
	v_mfma_f32_16x16x32_bf16 v[36:39], v[188:191], v[212:215], v[36:39]
	v_mfma_f32_16x16x32_bf16 v[32:35], v[196:199], v[212:215], v[32:35]
	v_mfma_f32_16x16x32_bf16 v[20:23], v[188:191], v[220:223], v[20:23]
	v_mfma_f32_16x16x32_bf16 v[16:19], v[196:199], v[220:223], v[16:19]
	v_mfma_f32_16x16x32_bf16 v[4:7], v[188:191], v[228:231], v[4:7]
	v_mfma_f32_16x16x32_bf16 v[0:3], v[196:199], v[228:231], v[0:3]
	s_setprio 0
	s_barrier
	v_add_u32_e32 v178, s29, v162
	v_add_u32_e32 v187, s41, v162
	ds_read_b128 v[166:169], v178
	ds_read_b128 v[170:173], v178 offset:1024
	ds_read_b128 v[174:177], v178 offset:2048
	ds_read_b128 v[178:181], v178 offset:3072
	ds_read_b128 v[182:185], v187
	ds_read_b128 v[188:191], v187 offset:1024
	ds_read_b128 v[192:195], v187 offset:2048
	ds_read_b128 v[196:199], v187 offset:3072
	s_mov_b32 m0, s89
	s_add_u32 s100, s44, 0x80
	s_addc_u32 s101, s45, 0
	ds_read_b128 v[200:203], v165 offset:32768
	ds_read_b128 v[204:207], v165 offset:33792
	ds_read_b128 v[208:211], v165 offset:34816
	ds_read_b128 v[212:215], v165 offset:35840
	ds_read_b128 v[216:219], v165 offset:36864
	ds_read_b128 v[220:223], v165 offset:37888
	ds_read_b128 v[224:227], v165 offset:38912
	ds_read_b128 v[228:231], v165 offset:39936
	global_load_lds_dwordx4 v128, s[98:99]
	s_mov_b32 m0, s90
	s_add_u32 s54, s44, 0x80080
	s_addc_u32 s55, s45, 0
	global_load_lds_dwordx4 v132, s[98:99]
	s_add_u32 s98, s46, 0x80
	s_addc_u32 s99, s47, 0
	s_waitcnt vmcnt(8)
	s_waitcnt lgkmcnt(0)
	s_barrier
	s_setprio 1
	s_waitcnt lgkmcnt(0)
	v_mfma_f32_16x16x32_bf16 v[124:127], v[166:169], v[200:203], v[124:127]
	v_mfma_f32_16x16x32_bf16 v[120:123], v[174:177], v[200:203], v[120:123]
	v_mfma_f32_16x16x32_bf16 v[108:111], v[166:169], v[208:211], v[108:111]
	v_mfma_f32_16x16x32_bf16 v[104:107], v[174:177], v[208:211], v[104:107]
	v_mfma_f32_16x16x32_bf16 v[92:95], v[166:169], v[216:219], v[92:95]
	v_mfma_f32_16x16x32_bf16 v[88:91], v[174:177], v[216:219], v[88:91]
	v_mfma_f32_16x16x32_bf16 v[76:79], v[166:169], v[224:227], v[76:79]
	v_mfma_f32_16x16x32_bf16 v[72:75], v[174:177], v[224:227], v[72:75]
	v_mfma_f32_16x16x32_bf16 v[124:127], v[170:173], v[204:207], v[124:127]
	v_mfma_f32_16x16x32_bf16 v[120:123], v[178:181], v[204:207], v[120:123]
	v_mfma_f32_16x16x32_bf16 v[108:111], v[170:173], v[212:215], v[108:111]
	v_mfma_f32_16x16x32_bf16 v[104:107], v[178:181], v[212:215], v[104:107]
	v_mfma_f32_16x16x32_bf16 v[92:95], v[170:173], v[220:223], v[92:95]
	v_mfma_f32_16x16x32_bf16 v[88:91], v[178:181], v[220:223], v[88:91]
	v_mfma_f32_16x16x32_bf16 v[76:79], v[170:173], v[228:231], v[76:79]
	v_mfma_f32_16x16x32_bf16 v[72:75], v[178:181], v[228:231], v[72:75]
	v_mfma_f32_16x16x32_bf16 v[116:119], v[182:185], v[200:203], v[116:119]
	v_mfma_f32_16x16x32_bf16 v[112:115], v[192:195], v[200:203], v[112:115]
	v_mfma_f32_16x16x32_bf16 v[100:103], v[182:185], v[208:211], v[100:103]
	v_mfma_f32_16x16x32_bf16 v[96:99], v[192:195], v[208:211], v[96:99]
	v_mfma_f32_16x16x32_bf16 v[84:87], v[182:185], v[216:219], v[84:87]
	v_mfma_f32_16x16x32_bf16 v[80:83], v[192:195], v[216:219], v[80:83]
	v_mfma_f32_16x16x32_bf16 v[68:71], v[182:185], v[224:227], v[68:71]
	v_mfma_f32_16x16x32_bf16 v[64:67], v[192:195], v[224:227], v[64:67]
	v_mfma_f32_16x16x32_bf16 v[116:119], v[188:191], v[204:207], v[116:119]
	v_mfma_f32_16x16x32_bf16 v[112:115], v[196:199], v[204:207], v[112:115]
	v_mfma_f32_16x16x32_bf16 v[100:103], v[188:191], v[212:215], v[100:103]
	v_mfma_f32_16x16x32_bf16 v[96:99], v[196:199], v[212:215], v[96:99]
	v_mfma_f32_16x16x32_bf16 v[84:87], v[188:191], v[220:223], v[84:87]
	v_mfma_f32_16x16x32_bf16 v[80:83], v[196:199], v[220:223], v[80:83]
	v_mfma_f32_16x16x32_bf16 v[68:71], v[188:191], v[228:231], v[68:71]
	v_mfma_f32_16x16x32_bf16 v[64:67], v[196:199], v[228:231], v[64:67]
	s_setprio 0
	s_barrier
	s_mov_b32 m0, s27
	s_nop 0
	ds_read_b128 v[200:203], v165 offset:49152
	ds_read_b128 v[204:207], v165 offset:50176
	ds_read_b128 v[208:211], v165 offset:51200
	ds_read_b128 v[212:215], v165 offset:52224
	ds_read_b128 v[216:219], v165 offset:53248
	ds_read_b128 v[220:223], v165 offset:54272
	ds_read_b128 v[224:227], v165 offset:55296
	ds_read_b128 v[228:231], v165 offset:56320
	global_load_lds_dwordx4 v130, s[100:101]
	s_mov_b32 m0, s34
	s_nop 0
	global_load_lds_dwordx4 v134, s[100:101]
	s_mov_b32 m0, s35
	s_nop 0
	global_load_lds_dwordx4 v130, s[54:55]
	s_mov_b32 m0, s28
	s_nop 0
	global_load_lds_dwordx4 v134, s[54:55]
	s_mov_b32 m0, s92
	s_nop 0
	global_load_lds_dwordx4 v128, s[98:99]
	s_mov_b32 m0, s93
	s_nop 0
	global_load_lds_dwordx4 v132, s[98:99]
	s_waitcnt vmcnt(8)
	s_waitcnt lgkmcnt(0)
	s_barrier
	s_setprio 1
	s_waitcnt lgkmcnt(0)
	v_mfma_f32_16x16x32_bf16 v[60:63], v[166:169], v[200:203], v[60:63]
	v_mfma_f32_16x16x32_bf16 v[56:59], v[174:177], v[200:203], v[56:59]
	v_mfma_f32_16x16x32_bf16 v[44:47], v[166:169], v[208:211], v[44:47]
	v_mfma_f32_16x16x32_bf16 v[40:43], v[174:177], v[208:211], v[40:43]
	v_mfma_f32_16x16x32_bf16 v[28:31], v[166:169], v[216:219], v[28:31]
	v_mfma_f32_16x16x32_bf16 v[24:27], v[174:177], v[216:219], v[24:27]
	v_mfma_f32_16x16x32_bf16 v[12:15], v[166:169], v[224:227], v[12:15]
	v_mfma_f32_16x16x32_bf16 v[8:11], v[174:177], v[224:227], v[8:11]
	v_mfma_f32_16x16x32_bf16 v[60:63], v[170:173], v[204:207], v[60:63]
	v_mfma_f32_16x16x32_bf16 v[56:59], v[178:181], v[204:207], v[56:59]
	v_mfma_f32_16x16x32_bf16 v[44:47], v[170:173], v[212:215], v[44:47]
	v_mfma_f32_16x16x32_bf16 v[40:43], v[178:181], v[212:215], v[40:43]
	v_mfma_f32_16x16x32_bf16 v[28:31], v[170:173], v[220:223], v[28:31]
	v_mfma_f32_16x16x32_bf16 v[24:27], v[178:181], v[220:223], v[24:27]
	v_mfma_f32_16x16x32_bf16 v[12:15], v[170:173], v[228:231], v[12:15]
	v_mfma_f32_16x16x32_bf16 v[8:11], v[178:181], v[228:231], v[8:11]
	v_mfma_f32_16x16x32_bf16 v[52:55], v[182:185], v[200:203], v[52:55]
	v_mfma_f32_16x16x32_bf16 v[48:51], v[192:195], v[200:203], v[48:51]
	v_mfma_f32_16x16x32_bf16 v[36:39], v[182:185], v[208:211], v[36:39]
	v_mfma_f32_16x16x32_bf16 v[32:35], v[192:195], v[208:211], v[32:35]
	v_mfma_f32_16x16x32_bf16 v[20:23], v[182:185], v[216:219], v[20:23]
	v_mfma_f32_16x16x32_bf16 v[16:19], v[192:195], v[216:219], v[16:19]
	v_mfma_f32_16x16x32_bf16 v[4:7], v[182:185], v[224:227], v[4:7]
	v_mfma_f32_16x16x32_bf16 v[0:3], v[192:195], v[224:227], v[0:3]
	v_mfma_f32_16x16x32_bf16 v[52:55], v[188:191], v[204:207], v[52:55]
	v_mfma_f32_16x16x32_bf16 v[48:51], v[196:199], v[204:207], v[48:51]
	v_mfma_f32_16x16x32_bf16 v[36:39], v[188:191], v[212:215], v[36:39]
	v_mfma_f32_16x16x32_bf16 v[32:35], v[196:199], v[212:215], v[32:35]
	v_mfma_f32_16x16x32_bf16 v[20:23], v[188:191], v[220:223], v[20:23]
	v_mfma_f32_16x16x32_bf16 v[16:19], v[196:199], v[220:223], v[16:19]
	v_mfma_f32_16x16x32_bf16 v[4:7], v[188:191], v[228:231], v[4:7]
	v_mfma_f32_16x16x32_bf16 v[0:3], v[196:199], v[228:231], v[0:3]
	s_setprio 0
	s_barrier
	s_add_i32 s52, s52, 2
	s_add_u32 s42, s42, 0x100
	s_addc_u32 s43, s43, 0
	s_add_u32 s17, s17, 0x100
	s_addc_u32 s21, s21, 0
	s_cmp_gt_u32 s52, 29
	s_cbranch_scc0 .LBB0_507
	s_and_b64 vcc, exec, s[78:79]
	s_cbranch_vccz .LBB0_510
	s_barrier

.LBB0_674:
	ds_read_b128 v[128:131], v174
	ds_read_b128 v[132:135], v174 offset:1024
	ds_read_b128 v[148:151], v174 offset:2048
	ds_read_b128 v[152:155], v174 offset:3072
	ds_read_b128 v[156:159], v175
	ds_read_b128 v[160:163], v175 offset:1024
	ds_read_b128 v[164:167], v175 offset:2048
	ds_read_b128 v[168:171], v175 offset:3072
	s_add_u32 s36, s24, 0x4000
	s_addc_u32 s37, s25, 0
	s_cmpk_eq_i32 s45, 0x7c
	s_cselect_b32 s40, s29, s36
	s_cselect_b32 s41, s3, s37
	s_cselect_b32 s38, s4, s30
	s_cselect_b32 s39, s5, s31
	s_add_u32 s36, s40, 0x8000
	s_addc_u32 s37, s41, 0
	s_mov_b32 m0, s94
	v_lshl_add_u64 v[216:217], s[24:25], 0, v[144:145]
	ds_read_b128 v[182:185], v176
	ds_read_b128 v[188:191], v176 offset:1024
	ds_read_b128 v[192:195], v176 offset:2048
	ds_read_b128 v[196:199], v176 offset:3072
	ds_read_b128 v[200:203], v176 offset:4096
	ds_read_b128 v[204:207], v176 offset:5120
	ds_read_b128 v[208:211], v176 offset:6144
	ds_read_b128 v[212:215], v176 offset:7168
	global_load_lds_dwordx4 v[216:217], off
	v_lshl_add_u64 v[216:217], s[24:25], 0, v[146:147]
	s_mov_b32 m0, s95
	s_nop 0
	global_load_lds_dwordx4 v[216:217], off
	s_waitcnt vmcnt(8)
	s_waitcnt lgkmcnt(0)
	s_barrier
	s_setprio 1
	s_waitcnt lgkmcnt(0)
	v_mfma_f32_16x16x32_bf16 v[124:127], v[128:131], v[182:185], v[124:127]
	v_mfma_f32_16x16x32_bf16 v[120:123], v[148:151], v[182:185], v[120:123]
	v_mfma_f32_16x16x32_bf16 v[108:111], v[128:131], v[192:195], v[108:111]
	v_mfma_f32_16x16x32_bf16 v[104:107], v[148:151], v[192:195], v[104:107]
	v_mfma_f32_16x16x32_bf16 v[92:95], v[128:131], v[200:203], v[92:95]
	v_mfma_f32_16x16x32_bf16 v[88:91], v[148:151], v[200:203], v[88:91]
	v_mfma_f32_16x16x32_bf16 v[76:79], v[128:131], v[208:211], v[76:79]
	v_mfma_f32_16x16x32_bf16 v[72:75], v[148:151], v[208:211], v[72:75]
	v_mfma_f32_16x16x32_bf16 v[124:127], v[132:135], v[188:191], v[124:127]
	v_mfma_f32_16x16x32_bf16 v[120:123], v[152:155], v[188:191], v[120:123]
	v_mfma_f32_16x16x32_bf16 v[108:111], v[132:135], v[196:199], v[108:111]
	v_mfma_f32_16x16x32_bf16 v[104:107], v[152:155], v[196:199], v[104:107]
	v_mfma_f32_16x16x32_bf16 v[92:95], v[132:135], v[204:207], v[92:95]
	v_mfma_f32_16x16x32_bf16 v[88:91], v[152:155], v[204:207], v[88:91]
	v_mfma_f32_16x16x32_bf16 v[76:79], v[132:135], v[212:215], v[76:79]
	v_mfma_f32_16x16x32_bf16 v[72:75], v[152:155], v[212:215], v[72:75]
	v_mfma_f32_16x16x32_bf16 v[116:119], v[156:159], v[182:185], v[116:119]
	v_mfma_f32_16x16x32_bf16 v[112:115], v[164:167], v[182:185], v[112:115]
	v_mfma_f32_16x16x32_bf16 v[100:103], v[156:159], v[192:195], v[100:103]
	v_mfma_f32_16x16x32_bf16 v[96:99], v[164:167], v[192:195], v[96:99]
	v_mfma_f32_16x16x32_bf16 v[84:87], v[156:159], v[200:203], v[84:87]
	v_mfma_f32_16x16x32_bf16 v[80:83], v[164:167], v[200:203], v[80:83]
	v_mfma_f32_16x16x32_bf16 v[68:71], v[156:159], v[208:211], v[68:71]
	v_mfma_f32_16x16x32_bf16 v[64:67], v[164:167], v[208:211], v[64:67]
	v_mfma_f32_16x16x32_bf16 v[116:119], v[160:163], v[188:191], v[116:119]
	v_mfma_f32_16x16x32_bf16 v[112:115], v[168:171], v[188:191], v[112:115]
	v_mfma_f32_16x16x32_bf16 v[100:103], v[160:163], v[196:199], v[100:103]
	v_mfma_f32_16x16x32_bf16 v[96:99], v[168:171], v[196:199], v[96:99]
	v_mfma_f32_16x16x32_bf16 v[84:87], v[160:163], v[204:207], v[84:87]
	v_mfma_f32_16x16x32_bf16 v[80:83], v[168:171], v[204:207], v[80:83]
	v_mfma_f32_16x16x32_bf16 v[68:71], v[160:163], v[212:215], v[68:71]
	v_mfma_f32_16x16x32_bf16 v[64:67], v[168:171], v[212:215], v[64:67]
	s_setprio 0
	s_barrier
	s_mov_b32 m0, s96
	v_lshl_add_u64 v[216:217], s[38:39], 0, v[138:139]
	s_add_u32 s46, s38, 0x200000
	ds_read_b128 v[182:185], v176 offset:16384
	ds_read_b128 v[188:191], v176 offset:17408
	ds_read_b128 v[192:195], v176 offset:18432
	ds_read_b128 v[196:199], v176 offset:19456
	ds_read_b128 v[200:203], v176 offset:20480
	ds_read_b128 v[204:207], v176 offset:21504
	ds_read_b128 v[208:211], v176 offset:22528
	ds_read_b128 v[212:215], v176 offset:23552
	global_load_lds_dwordx4 v[216:217], off
	v_lshl_add_u64 v[218:219], s[38:39], 0, v[142:143]
	s_mov_b32 m0, s97
	s_addc_u32 s47, s39, 0
	global_load_lds_dwordx4 v[218:219], off
	v_lshl_add_u64 v[220:221], s[46:47], 0, v[138:139]
	s_mov_b32 m0, s91
	s_nop 0
	global_load_lds_dwordx4 v[220:221], off
	v_lshl_add_u64 v[220:221], s[46:47], 0, v[142:143]
	s_mov_b32 m0, s26
	s_nop 0
	global_load_lds_dwordx4 v[220:221], off
	v_lshl_add_u64 v[220:221], s[40:41], 0, v[136:137]
	s_mov_b32 m0, s33
	s_nop 0
	global_load_lds_dwordx4 v[220:221], off
	v_lshl_add_u64 v[220:221], s[40:41], 0, v[140:141]
	s_mov_b32 m0, s88
	s_nop 0
	global_load_lds_dwordx4 v[220:221], off
	s_waitcnt vmcnt(8)
	s_waitcnt lgkmcnt(0)
	s_barrier
	s_setprio 1
	s_waitcnt lgkmcnt(0)
	v_mfma_f32_16x16x32_bf16 v[60:63], v[128:131], v[182:185], v[60:63]
	v_mfma_f32_16x16x32_bf16 v[56:59], v[148:151], v[182:185], v[56:59]
	v_mfma_f32_16x16x32_bf16 v[44:47], v[128:131], v[192:195], v[44:47]
	v_mfma_f32_16x16x32_bf16 v[40:43], v[148:151], v[192:195], v[40:43]
	v_mfma_f32_16x16x32_bf16 v[28:31], v[128:131], v[200:203], v[28:31]
	v_mfma_f32_16x16x32_bf16 v[24:27], v[148:151], v[200:203], v[24:27]
	v_mfma_f32_16x16x32_bf16 v[12:15], v[128:131], v[208:211], v[12:15]
	v_mfma_f32_16x16x32_bf16 v[8:11], v[148:151], v[208:211], v[8:11]
	v_mfma_f32_16x16x32_bf16 v[60:63], v[132:135], v[188:191], v[60:63]
	v_mfma_f32_16x16x32_bf16 v[56:59], v[152:155], v[188:191], v[56:59]
	v_mfma_f32_16x16x32_bf16 v[44:47], v[132:135], v[196:199], v[44:47]
	v_mfma_f32_16x16x32_bf16 v[40:43], v[152:155], v[196:199], v[40:43]
	v_mfma_f32_16x16x32_bf16 v[28:31], v[132:135], v[204:207], v[28:31]
	v_mfma_f32_16x16x32_bf16 v[24:27], v[152:155], v[204:207], v[24:27]
	v_mfma_f32_16x16x32_bf16 v[12:15], v[132:135], v[212:215], v[12:15]
	v_mfma_f32_16x16x32_bf16 v[8:11], v[152:155], v[212:215], v[8:11]
	v_mfma_f32_16x16x32_bf16 v[52:55], v[156:159], v[182:185], v[52:55]
	v_mfma_f32_16x16x32_bf16 v[48:51], v[164:167], v[182:185], v[48:51]
	v_mfma_f32_16x16x32_bf16 v[36:39], v[156:159], v[192:195], v[36:39]
	v_mfma_f32_16x16x32_bf16 v[32:35], v[164:167], v[192:195], v[32:35]
	v_mfma_f32_16x16x32_bf16 v[20:23], v[156:159], v[200:203], v[20:23]
	v_mfma_f32_16x16x32_bf16 v[16:19], v[164:167], v[200:203], v[16:19]
	v_mfma_f32_16x16x32_bf16 v[4:7], v[156:159], v[208:211], v[4:7]
	v_mfma_f32_16x16x32_bf16 v[0:3], v[164:167], v[208:211], v[0:3]
	v_mfma_f32_16x16x32_bf16 v[52:55], v[160:163], v[188:191], v[52:55]
	v_mfma_f32_16x16x32_bf16 v[48:51], v[168:171], v[188:191], v[48:51]
	v_mfma_f32_16x16x32_bf16 v[36:39], v[160:163], v[196:199], v[36:39]
	v_mfma_f32_16x16x32_bf16 v[32:35], v[168:171], v[196:199], v[32:35]
	v_mfma_f32_16x16x32_bf16 v[20:23], v[160:163], v[204:207], v[20:23]
	v_mfma_f32_16x16x32_bf16 v[16:19], v[168:171], v[204:207], v[16:19]
	v_mfma_f32_16x16x32_bf16 v[4:7], v[160:163], v[212:215], v[4:7]
	v_mfma_f32_16x16x32_bf16 v[0:3], v[168:171], v[212:215], v[0:3]
	s_setprio 0
	s_barrier
	ds_read_b128 v[128:131], v179
	ds_read_b128 v[132:135], v179 offset:1024
	ds_read_b128 v[148:151], v179 offset:2048
	ds_read_b128 v[152:155], v179 offset:3072
	ds_read_b128 v[156:159], v180
	ds_read_b128 v[160:163], v180 offset:1024
	ds_read_b128 v[164:167], v180 offset:2048
	ds_read_b128 v[168:171], v180 offset:3072
	s_add_u32 s40, s40, 0x4000
	s_addc_u32 s41, s41, 0
	s_mov_b32 m0, s89
	v_lshl_add_u64 v[220:221], s[40:41], 0, v[136:137]
	ds_read_b128 v[182:185], v176 offset:32768
	ds_read_b128 v[188:191], v176 offset:33792
	ds_read_b128 v[192:195], v176 offset:34816
	ds_read_b128 v[196:199], v176 offset:35840
	ds_read_b128 v[200:203], v176 offset:36864
	ds_read_b128 v[204:207], v176 offset:37888
	ds_read_b128 v[208:211], v176 offset:38912
	ds_read_b128 v[212:215], v176 offset:39936
	global_load_lds_dwordx4 v[220:221], off
	v_lshl_add_u64 v[220:221], s[40:41], 0, v[140:141]
	s_mov_b32 m0, s90
	s_nop 0
	global_load_lds_dwordx4 v[220:221], off
	s_waitcnt vmcnt(8)
	s_waitcnt lgkmcnt(0)
	s_barrier
	s_setprio 1
	s_waitcnt lgkmcnt(0)
	v_mfma_f32_16x16x32_bf16 v[124:127], v[128:131], v[182:185], v[124:127]
	v_mfma_f32_16x16x32_bf16 v[120:123], v[148:151], v[182:185], v[120:123]
	v_mfma_f32_16x16x32_bf16 v[108:111], v[128:131], v[192:195], v[108:111]
	v_mfma_f32_16x16x32_bf16 v[104:107], v[148:151], v[192:195], v[104:107]
	v_mfma_f32_16x16x32_bf16 v[92:95], v[128:131], v[200:203], v[92:95]
	v_mfma_f32_16x16x32_bf16 v[88:91], v[148:151], v[200:203], v[88:91]
	v_mfma_f32_16x16x32_bf16 v[76:79], v[128:131], v[208:211], v[76:79]
	v_mfma_f32_16x16x32_bf16 v[72:75], v[148:151], v[208:211], v[72:75]
	v_mfma_f32_16x16x32_bf16 v[124:127], v[132:135], v[188:191], v[124:127]
	v_mfma_f32_16x16x32_bf16 v[120:123], v[152:155], v[188:191], v[120:123]
	v_mfma_f32_16x16x32_bf16 v[108:111], v[132:135], v[196:199], v[108:111]
	v_mfma_f32_16x16x32_bf16 v[104:107], v[152:155], v[196:199], v[104:107]
	v_mfma_f32_16x16x32_bf16 v[92:95], v[132:135], v[204:207], v[92:95]
	v_mfma_f32_16x16x32_bf16 v[88:91], v[152:155], v[204:207], v[88:91]
	v_mfma_f32_16x16x32_bf16 v[76:79], v[132:135], v[212:215], v[76:79]
	v_mfma_f32_16x16x32_bf16 v[72:75], v[152:155], v[212:215], v[72:75]
	v_mfma_f32_16x16x32_bf16 v[116:119], v[156:159], v[182:185], v[116:119]
	v_mfma_f32_16x16x32_bf16 v[112:115], v[164:167], v[182:185], v[112:115]
	v_mfma_f32_16x16x32_bf16 v[100:103], v[156:159], v[192:195], v[100:103]
	v_mfma_f32_16x16x32_bf16 v[96:99], v[164:167], v[192:195], v[96:99]
	v_mfma_f32_16x16x32_bf16 v[84:87], v[156:159], v[200:203], v[84:87]
	v_mfma_f32_16x16x32_bf16 v[80:83], v[164:167], v[200:203], v[80:83]
	v_mfma_f32_16x16x32_bf16 v[68:71], v[156:159], v[208:211], v[68:71]
	v_mfma_f32_16x16x32_bf16 v[64:67], v[164:167], v[208:211], v[64:67]
	v_mfma_f32_16x16x32_bf16 v[116:119], v[160:163], v[188:191], v[116:119]
	v_mfma_f32_16x16x32_bf16 v[112:115], v[168:171], v[188:191], v[112:115]
	v_mfma_f32_16x16x32_bf16 v[100:103], v[160:163], v[196:199], v[100:103]
	v_mfma_f32_16x16x32_bf16 v[96:99], v[168:171], v[196:199], v[96:99]
	v_mfma_f32_16x16x32_bf16 v[84:87], v[160:163], v[204:207], v[84:87]
	v_mfma_f32_16x16x32_bf16 v[80:83], v[168:171], v[204:207], v[80:83]
	v_mfma_f32_16x16x32_bf16 v[68:71], v[160:163], v[212:215], v[68:71]
	v_mfma_f32_16x16x32_bf16 v[64:67], v[168:171], v[212:215], v[64:67]
	s_setprio 0
	s_barrier
	s_mov_b32 m0, s27
	v_lshl_add_u64 v[216:217], v[216:217], 0, s[6:7]
	s_add_u32 s38, s38, 0x200080
	ds_read_b128 v[182:185], v176 offset:49152
	ds_read_b128 v[188:191], v176 offset:50176
	ds_read_b128 v[192:195], v176 offset:51200
	ds_read_b128 v[196:199], v176 offset:52224
	ds_read_b128 v[200:203], v176 offset:53248
	ds_read_b128 v[204:207], v176 offset:54272
	ds_read_b128 v[208:211], v176 offset:55296
	ds_read_b128 v[212:215], v176 offset:56320
	global_load_lds_dwordx4 v[216:217], off
	v_lshl_add_u64 v[216:217], v[218:219], 0, s[6:7]
	s_mov_b32 m0, s34
	s_addc_u32 s39, s39, 0
	global_load_lds_dwordx4 v[216:217], off
	v_lshl_add_u64 v[216:217], s[38:39], 0, v[138:139]
	s_mov_b32 m0, s35
	s_nop 0
	global_load_lds_dwordx4 v[216:217], off
	v_lshl_add_u64 v[216:217], s[38:39], 0, v[142:143]
	s_mov_b32 m0, s28
	s_nop 0
	global_load_lds_dwordx4 v[216:217], off
	v_lshl_add_u64 v[216:217], s[36:37], 0, v[136:137]
	s_mov_b32 m0, s92
	s_nop 0
	global_load_lds_dwordx4 v[216:217], off
	v_lshl_add_u64 v[216:217], s[36:37], 0, v[140:141]
	s_mov_b32 m0, s93
	s_nop 0
	global_load_lds_dwordx4 v[216:217], off
	s_waitcnt vmcnt(8)
	s_waitcnt lgkmcnt(0)
	s_barrier
	s_setprio 1
	s_waitcnt lgkmcnt(0)
	v_mfma_f32_16x16x32_bf16 v[60:63], v[128:131], v[182:185], v[60:63]
	v_mfma_f32_16x16x32_bf16 v[56:59], v[148:151], v[182:185], v[56:59]
	v_mfma_f32_16x16x32_bf16 v[44:47], v[128:131], v[192:195], v[44:47]
	v_mfma_f32_16x16x32_bf16 v[40:43], v[148:151], v[192:195], v[40:43]
	v_mfma_f32_16x16x32_bf16 v[28:31], v[128:131], v[200:203], v[28:31]
	v_mfma_f32_16x16x32_bf16 v[24:27], v[148:151], v[200:203], v[24:27]
	v_mfma_f32_16x16x32_bf16 v[12:15], v[128:131], v[208:211], v[12:15]
	v_mfma_f32_16x16x32_bf16 v[8:11], v[148:151], v[208:211], v[8:11]
	v_mfma_f32_16x16x32_bf16 v[60:63], v[132:135], v[188:191], v[60:63]
	v_mfma_f32_16x16x32_bf16 v[56:59], v[152:155], v[188:191], v[56:59]
	v_mfma_f32_16x16x32_bf16 v[44:47], v[132:135], v[196:199], v[44:47]
	v_mfma_f32_16x16x32_bf16 v[40:43], v[152:155], v[196:199], v[40:43]
	v_mfma_f32_16x16x32_bf16 v[28:31], v[132:135], v[204:207], v[28:31]
	v_mfma_f32_16x16x32_bf16 v[24:27], v[152:155], v[204:207], v[24:27]
	v_mfma_f32_16x16x32_bf16 v[12:15], v[132:135], v[212:215], v[12:15]
	v_mfma_f32_16x16x32_bf16 v[8:11], v[152:155], v[212:215], v[8:11]
	v_mfma_f32_16x16x32_bf16 v[52:55], v[156:159], v[182:185], v[52:55]
	v_mfma_f32_16x16x32_bf16 v[48:51], v[164:167], v[182:185], v[48:51]
	v_mfma_f32_16x16x32_bf16 v[36:39], v[156:159], v[192:195], v[36:39]
	v_mfma_f32_16x16x32_bf16 v[32:35], v[164:167], v[192:195], v[32:35]
	v_mfma_f32_16x16x32_bf16 v[20:23], v[156:159], v[200:203], v[20:23]
	v_mfma_f32_16x16x32_bf16 v[16:19], v[164:167], v[200:203], v[16:19]
	v_mfma_f32_16x16x32_bf16 v[4:7], v[156:159], v[208:211], v[4:7]
	v_mfma_f32_16x16x32_bf16 v[0:3], v[164:167], v[208:211], v[0:3]
	v_mfma_f32_16x16x32_bf16 v[52:55], v[160:163], v[188:191], v[52:55]
	v_mfma_f32_16x16x32_bf16 v[48:51], v[168:171], v[188:191], v[48:51]
	v_mfma_f32_16x16x32_bf16 v[36:39], v[160:163], v[196:199], v[36:39]
	v_mfma_f32_16x16x32_bf16 v[32:35], v[168:171], v[196:199], v[32:35]
	v_mfma_f32_16x16x32_bf16 v[20:23], v[160:163], v[204:207], v[20:23]
	v_mfma_f32_16x16x32_bf16 v[16:19], v[168:171], v[204:207], v[16:19]
	v_mfma_f32_16x16x32_bf16 v[4:7], v[160:163], v[212:215], v[4:7]
	v_mfma_f32_16x16x32_bf16 v[0:3], v[168:171], v[212:215], v[0:3]
	s_setprio 0
	s_barrier
	s_add_i32 s45, s45, 2
	s_add_u32 s30, s30, 0x100
	s_addc_u32 s31, s31, 0
	s_add_u32 s24, s24, 0x10000
	s_addc_u32 s25, s25, 0
	s_cmpk_gt_u32 s45, 0x7d
	s_cbranch_scc0 .LBB0_674
	s_and_b64 vcc, exec, s[78:79]
	s_cbranch_vccz .LBB0_677
	s_barrier
